# sc1 (write-through) also on the last phase's f32 output stores (less dirty L2 data at kernel end)
# baseline (speedup 1.0000x reference)
.LBB0_598:
	v_lshl_add_u32 v162, s65, 8, v3
	v_lshl_or_b32 v178, s68, 8, v171
	v_ashrrev_i32_e32 v179, 31, v178
	v_ashrrev_i32_e32 v163, 31, v162
	v_lshl_add_u64 v[160:161], v[178:179], 1, s[42:43]
	v_lshlrev_b64 v[132:133], 11, v[162:163]
	v_lshl_add_u64 v[132:133], v[160:161], 0, v[132:133]
	global_load_dwordx4 v[174:177], v[132:133], off nt
	global_load_dwordx4 v[190:193], v[132:133], off offset:256 nt
	v_or_b32_e32 v168, 16, v162
	v_ashrrev_i32_e32 v169, 31, v168
	v_lshlrev_b64 v[132:133], 11, v[168:169]
	v_lshl_add_u64 v[132:133], v[160:161], 0, v[132:133]
	global_load_dwordx4 v[194:197], v[132:133], off nt
	global_load_dwordx4 v[148:151], v[132:133], off offset:256 nt
	v_or_b32_e32 v166, 32, v162
	v_ashrrev_i32_e32 v167, 31, v166
	v_lshlrev_b64 v[132:133], 11, v[166:167]
	v_lshl_add_u64 v[132:133], v[160:161], 0, v[132:133]
	global_load_dwordx4 v[144:147], v[132:133], off nt
	global_load_dwordx4 v[140:143], v[132:133], off offset:256 nt
	v_or_b32_e32 v164, 48, v162
	v_ashrrev_i32_e32 v165, 31, v164
	v_lshlrev_b64 v[132:133], 11, v[164:165]
	v_lshl_add_u64 v[132:133], v[160:161], 0, v[132:133]
	global_load_dwordx4 v[136:139], v[132:133], off nt
	s_nop 0
	global_load_dwordx4 v[132:135], v[132:133], off offset:256 nt
	v_readlane_b32 s68, v251, 4
	v_readlane_b32 s82, v251, 18
	v_readlane_b32 s83, v251, 19
	s_mov_b64 s[26:27], -1
	s_and_b64 vcc, exec, s[6:7]
	v_readlane_b32 s69, v251, 5
	v_readlane_b32 s70, v251, 6
	v_readlane_b32 s71, v251, 7
	v_readlane_b32 s72, v251, 8
	v_readlane_b32 s73, v251, 9
	v_readlane_b32 s74, v251, 10
	v_readlane_b32 s75, v251, 11
	v_readlane_b32 s76, v251, 12
	v_readlane_b32 s77, v251, 13
	v_readlane_b32 s78, v251, 14
	v_readlane_b32 s79, v251, 15
	v_readlane_b32 s80, v251, 16
	v_readlane_b32 s81, v251, 17
	s_waitcnt vmcnt(0)
	v_lshlrev_b32_e32 v182, 16, v174
	v_and_b32_e32 v183, 0xffff0000, v174
	v_lshlrev_b32_e32 v174, 16, v175
	v_and_b32_e32 v175, 0xffff0000, v175
	v_lshlrev_b32_e32 v184, 16, v176
	v_and_b32_e32 v185, 0xffff0000, v176
	v_lshlrev_b32_e32 v176, 16, v177
	v_and_b32_e32 v177, 0xffff0000, v177
	v_pk_fma_f32 v[130:131], v[130:131], 0.5, v[174:175] op_sel_hi:[1,0,1]
	v_pk_fma_f32 v[174:175], v[124:125], 0.5, v[184:185] op_sel_hi:[1,0,1]
	v_lshlrev_b64 v[124:125], 12, v[162:163]
	v_pk_fma_f32 v[176:177], v[126:127], 0.5, v[176:177] op_sel_hi:[1,0,1]
	v_lshl_add_u64 v[126:127], s[82:83], 0, v[124:125]
	v_lshlrev_b64 v[124:125], 2, v[178:179]
	v_pk_fma_f32 v[128:129], v[128:129], 0.5, v[182:183] op_sel_hi:[1,0,1]
	v_lshl_add_u64 v[126:127], v[126:127], 0, v[124:125]
	global_store_dwordx4 v[126:127], v[128:131], off sc1
	global_store_dwordx4 v[126:127], v[174:177], off offset:16 sc1
	s_nop 0
	v_lshlrev_b32_e32 v128, 16, v190
	v_and_b32_e32 v129, 0xffff0000, v190
	v_lshlrev_b32_e32 v130, 16, v191
	v_and_b32_e32 v131, 0xffff0000, v191
	v_lshlrev_b32_e32 v174, 16, v192
	v_and_b32_e32 v175, 0xffff0000, v192
	v_lshlrev_b32_e32 v176, 16, v193
	v_and_b32_e32 v177, 0xffff0000, v193
	v_pk_fma_f32 v[114:115], v[114:115], 0.5, v[130:131] op_sel_hi:[1,0,1]
	v_pk_fma_f32 v[112:113], v[112:113], 0.5, v[128:129] op_sel_hi:[1,0,1]
	v_pk_fma_f32 v[110:111], v[110:111], 0.5, v[176:177] op_sel_hi:[1,0,1]
	v_pk_fma_f32 v[108:109], v[108:109], 0.5, v[174:175] op_sel_hi:[1,0,1]
	global_store_dwordx4 v[126:127], v[112:115], off offset:512 sc1
	global_store_dwordx4 v[126:127], v[108:111], off offset:528 sc1
	s_nop 0
	v_lshlrev_b32_e32 v112, 16, v196
	v_and_b32_e32 v113, 0xffff0000, v196
	v_pk_fma_f32 v[112:113], v[116:117], 0.5, v[112:113] op_sel_hi:[1,0,1]
	v_lshlrev_b64 v[116:117], 12, v[168:169]
	v_lshlrev_b32_e32 v108, 16, v194
	v_and_b32_e32 v109, 0xffff0000, v194
	v_lshlrev_b32_e32 v110, 16, v195
	v_and_b32_e32 v111, 0xffff0000, v195
	v_lshl_add_u64 v[116:117], s[82:83], 0, v[116:117]
	v_lshlrev_b32_e32 v114, 16, v197
	v_and_b32_e32 v115, 0xffff0000, v197
	v_pk_fma_f32 v[110:111], v[122:123], 0.5, v[110:111] op_sel_hi:[1,0,1]
	v_pk_fma_f32 v[108:109], v[120:121], 0.5, v[108:109] op_sel_hi:[1,0,1]
	v_lshl_add_u64 v[116:117], v[116:117], 0, v[124:125]
	v_pk_fma_f32 v[114:115], v[118:119], 0.5, v[114:115] op_sel_hi:[1,0,1]
	global_store_dwordx4 v[116:117], v[108:111], off sc1
	global_store_dwordx4 v[116:117], v[112:115], off offset:16 sc1
	s_nop 0
	v_lshlrev_b32_e32 v108, 16, v148
	v_and_b32_e32 v109, 0xffff0000, v148
	v_lshlrev_b32_e32 v110, 16, v149
	v_and_b32_e32 v111, 0xffff0000, v149
	v_lshlrev_b32_e32 v112, 16, v150
	v_and_b32_e32 v113, 0xffff0000, v150
	v_lshlrev_b32_e32 v114, 16, v151
	v_and_b32_e32 v115, 0xffff0000, v151
	v_pk_fma_f32 v[106:107], v[106:107], 0.5, v[110:111] op_sel_hi:[1,0,1]
	v_pk_fma_f32 v[104:105], v[104:105], 0.5, v[108:109] op_sel_hi:[1,0,1]
	v_pk_fma_f32 v[100:101], v[100:101], 0.5, v[112:113] op_sel_hi:[1,0,1]
	v_pk_fma_f32 v[102:103], v[102:103], 0.5, v[114:115] op_sel_hi:[1,0,1]
	global_store_dwordx4 v[116:117], v[104:107], off offset:512 sc1
	global_store_dwordx4 v[116:117], v[100:103], off offset:528 sc1
	s_nop 0
	v_lshlrev_b32_e32 v104, 16, v146
	v_lshlrev_b32_e32 v100, 16, v144
	v_and_b32_e32 v101, 0xffff0000, v144
	v_pk_fma_f32 v[96:97], v[96:97], 0.5, v[100:101] op_sel_hi:[1,0,1]
	v_lshlrev_b64 v[100:101], 12, v[166:167]
	v_lshlrev_b32_e32 v102, 16, v145
	v_and_b32_e32 v103, 0xffff0000, v145
	v_and_b32_e32 v105, 0xffff0000, v146
	v_lshlrev_b32_e32 v106, 16, v147
	v_and_b32_e32 v107, 0xffff0000, v147
	v_lshl_add_u64 v[100:101], s[82:83], 0, v[100:101]
	v_pk_fma_f32 v[98:99], v[98:99], 0.5, v[102:103] op_sel_hi:[1,0,1]
	v_pk_fma_f32 v[94:95], v[94:95], 0.5, v[106:107] op_sel_hi:[1,0,1]
	v_pk_fma_f32 v[92:93], v[92:93], 0.5, v[104:105] op_sel_hi:[1,0,1]
	v_lshl_add_u64 v[100:101], v[100:101], 0, v[124:125]
	global_store_dwordx4 v[100:101], v[96:99], off sc1
	global_store_dwordx4 v[100:101], v[92:95], off offset:16 sc1
	v_add_u32_e32 v102, 0x90, v162
	v_lshlrev_b32_e32 v96, 16, v142
	v_lshlrev_b32_e32 v92, 16, v140
	v_and_b32_e32 v93, 0xffff0000, v140
	v_lshlrev_b32_e32 v94, 16, v141
	v_and_b32_e32 v95, 0xffff0000, v141
	v_and_b32_e32 v97, 0xffff0000, v142
	v_lshlrev_b32_e32 v98, 16, v143
	v_and_b32_e32 v99, 0xffff0000, v143
	v_pk_fma_f32 v[90:91], v[90:91], 0.5, v[94:95] op_sel_hi:[1,0,1]
	v_pk_fma_f32 v[88:89], v[88:89], 0.5, v[92:93] op_sel_hi:[1,0,1]
	v_pk_fma_f32 v[80:81], v[80:81], 0.5, v[96:97] op_sel_hi:[1,0,1]
	v_pk_fma_f32 v[82:83], v[82:83], 0.5, v[98:99] op_sel_hi:[1,0,1]
	global_store_dwordx4 v[100:101], v[88:91], off offset:512 sc1
	global_store_dwordx4 v[100:101], v[80:83], off offset:528 sc1
	v_add_u32_e32 v100, 0x80, v162
	v_lshlrev_b32_e32 v88, 16, v138
	v_lshlrev_b32_e32 v80, 16, v136
	v_and_b32_e32 v81, 0xffff0000, v136
	v_pk_fma_f32 v[80:81], v[84:85], 0.5, v[80:81] op_sel_hi:[1,0,1]
	v_lshlrev_b64 v[84:85], 12, v[164:165]
	v_lshlrev_b32_e32 v82, 16, v137
	v_and_b32_e32 v83, 0xffff0000, v137
	v_and_b32_e32 v89, 0xffff0000, v138
	v_lshlrev_b32_e32 v90, 16, v139
	v_and_b32_e32 v91, 0xffff0000, v139
	v_lshl_add_u64 v[84:85], s[82:83], 0, v[84:85]
	v_pk_fma_f32 v[82:83], v[86:87], 0.5, v[82:83] op_sel_hi:[1,0,1]
	v_pk_fma_f32 v[78:79], v[78:79], 0.5, v[90:91] op_sel_hi:[1,0,1]
	v_pk_fma_f32 v[76:77], v[76:77], 0.5, v[88:89] op_sel_hi:[1,0,1]
	v_lshl_add_u64 v[84:85], v[84:85], 0, v[124:125]
	global_store_dwordx4 v[84:85], v[80:83], off sc1
	global_store_dwordx4 v[84:85], v[76:79], off offset:16 sc1
	v_ashrrev_i32_e32 v101, 31, v100
	v_lshlrev_b32_e32 v80, 16, v134
	v_lshlrev_b32_e32 v76, 16, v132
	v_and_b32_e32 v77, 0xffff0000, v132
	v_lshlrev_b32_e32 v78, 16, v133
	v_and_b32_e32 v79, 0xffff0000, v133
	v_and_b32_e32 v81, 0xffff0000, v134
	v_lshlrev_b32_e32 v82, 16, v135
	v_and_b32_e32 v83, 0xffff0000, v135
	v_pk_fma_f32 v[74:75], v[74:75], 0.5, v[78:79] op_sel_hi:[1,0,1]
	v_pk_fma_f32 v[72:73], v[72:73], 0.5, v[76:77] op_sel_hi:[1,0,1]
	v_pk_fma_f32 v[68:69], v[68:69], 0.5, v[80:81] op_sel_hi:[1,0,1]
	v_pk_fma_f32 v[70:71], v[70:71], 0.5, v[82:83] op_sel_hi:[1,0,1]
	global_store_dwordx4 v[84:85], v[72:75], off offset:512 sc1
	global_store_dwordx4 v[84:85], v[68:71], off offset:528 sc1
	v_ashrrev_i32_e32 v103, 31, v102
	v_add_u32_e32 v104, 0xa0, v162
	v_lshlrev_b64 v[68:69], 11, v[100:101]
	v_lshl_add_u64 v[68:69], v[160:161], 0, v[68:69]
	global_load_dwordx4 v[72:75], v[68:69], off nt
	global_load_dwordx4 v[76:79], v[68:69], off offset:256 nt
	v_lshlrev_b64 v[68:69], 11, v[102:103]
	v_lshl_add_u64 v[68:69], v[160:161], 0, v[68:69]
	global_load_dwordx4 v[80:83], v[68:69], off nt
	global_load_dwordx4 v[84:87], v[68:69], off offset:256 nt
	v_ashrrev_i32_e32 v105, 31, v104
	v_lshlrev_b64 v[68:69], 11, v[104:105]
	v_lshl_add_u64 v[68:69], v[160:161], 0, v[68:69]
	global_load_dwordx4 v[88:91], v[68:69], off nt
	global_load_dwordx4 v[92:95], v[68:69], off offset:256 nt
	v_add_u32_e32 v106, 0xb0, v162
	v_ashrrev_i32_e32 v107, 31, v106
	v_lshlrev_b64 v[68:69], 11, v[106:107]
	v_lshl_add_u64 v[68:69], v[160:161], 0, v[68:69]
	global_load_dwordx4 v[96:99], v[68:69], off nt
	s_nop 0
	global_load_dwordx4 v[68:71], v[68:69], off offset:256 nt
	s_waitcnt vmcnt(7)
	v_lshlrev_b32_e32 v108, 16, v72
	v_and_b32_e32 v109, 0xffff0000, v72
	v_lshlrev_b32_e32 v72, 16, v73
	v_and_b32_e32 v73, 0xffff0000, v73
	v_pk_fma_f32 v[66:67], v[66:67], 0.5, v[72:73] op_sel_hi:[1,0,1]
	v_lshlrev_b64 v[72:73], 12, v[100:101]
	v_lshlrev_b32_e32 v110, 16, v74
	v_and_b32_e32 v111, 0xffff0000, v74
	v_lshlrev_b32_e32 v74, 16, v75
	v_and_b32_e32 v75, 0xffff0000, v75
	v_lshl_add_u64 v[72:73], s[82:83], 0, v[72:73]
	v_pk_fma_f32 v[64:65], v[64:65], 0.5, v[108:109] op_sel_hi:[1,0,1]
	v_pk_fma_f32 v[62:63], v[62:63], 0.5, v[74:75] op_sel_hi:[1,0,1]
	v_pk_fma_f32 v[60:61], v[60:61], 0.5, v[110:111] op_sel_hi:[1,0,1]
	v_lshl_add_u64 v[72:73], v[72:73], 0, v[124:125]
	global_store_dwordx4 v[72:73], v[64:67], off sc1
	global_store_dwordx4 v[72:73], v[60:63], off offset:16 sc1
	s_waitcnt vmcnt(8)
	v_lshlrev_b32_e32 v64, 16, v78
	v_lshlrev_b32_e32 v60, 16, v76
	v_and_b32_e32 v61, 0xffff0000, v76
	v_lshlrev_b32_e32 v62, 16, v77
	v_and_b32_e32 v63, 0xffff0000, v77
	v_and_b32_e32 v65, 0xffff0000, v78
	v_lshlrev_b32_e32 v66, 16, v79
	v_and_b32_e32 v67, 0xffff0000, v79
	v_pk_fma_f32 v[58:59], v[58:59], 0.5, v[62:63] op_sel_hi:[1,0,1]
	v_pk_fma_f32 v[56:57], v[56:57], 0.5, v[60:61] op_sel_hi:[1,0,1]
	v_pk_fma_f32 v[48:49], v[48:49], 0.5, v[64:65] op_sel_hi:[1,0,1]
	v_pk_fma_f32 v[50:51], v[50:51], 0.5, v[66:67] op_sel_hi:[1,0,1]
	global_store_dwordx4 v[72:73], v[56:59], off offset:512 sc1
	global_store_dwordx4 v[72:73], v[48:51], off offset:528 sc1
	s_waitcnt vmcnt(9)
	v_lshlrev_b32_e32 v56, 16, v82
	v_lshlrev_b32_e32 v48, 16, v80
	v_and_b32_e32 v49, 0xffff0000, v80
	v_pk_fma_f32 v[48:49], v[52:53], 0.5, v[48:49] op_sel_hi:[1,0,1]
	v_lshlrev_b64 v[52:53], 12, v[102:103]
	v_lshlrev_b32_e32 v50, 16, v81
	v_and_b32_e32 v51, 0xffff0000, v81
	v_and_b32_e32 v57, 0xffff0000, v82
	v_lshlrev_b32_e32 v58, 16, v83
	v_and_b32_e32 v59, 0xffff0000, v83
	v_lshl_add_u64 v[52:53], s[82:83], 0, v[52:53]
	v_pk_fma_f32 v[50:51], v[54:55], 0.5, v[50:51] op_sel_hi:[1,0,1]
	v_pk_fma_f32 v[46:47], v[46:47], 0.5, v[58:59] op_sel_hi:[1,0,1]
	v_pk_fma_f32 v[44:45], v[44:45], 0.5, v[56:57] op_sel_hi:[1,0,1]
	v_lshl_add_u64 v[52:53], v[52:53], 0, v[124:125]
	global_store_dwordx4 v[52:53], v[48:51], off sc1
	global_store_dwordx4 v[52:53], v[44:47], off offset:16 sc1
	s_waitcnt vmcnt(10)
	v_lshlrev_b32_e32 v48, 16, v86
	v_lshlrev_b32_e32 v44, 16, v84
	v_and_b32_e32 v45, 0xffff0000, v84
	v_lshlrev_b32_e32 v46, 16, v85
	v_and_b32_e32 v47, 0xffff0000, v85
	v_and_b32_e32 v49, 0xffff0000, v86
	v_lshlrev_b32_e32 v50, 16, v87
	v_and_b32_e32 v51, 0xffff0000, v87
	v_pk_fma_f32 v[42:43], v[42:43], 0.5, v[46:47] op_sel_hi:[1,0,1]
	v_pk_fma_f32 v[40:41], v[40:41], 0.5, v[44:45] op_sel_hi:[1,0,1]
	v_pk_fma_f32 v[32:33], v[32:33], 0.5, v[48:49] op_sel_hi:[1,0,1]
	v_pk_fma_f32 v[34:35], v[34:35], 0.5, v[50:51] op_sel_hi:[1,0,1]
	global_store_dwordx4 v[52:53], v[40:43], off offset:512 sc1
	global_store_dwordx4 v[52:53], v[32:35], off offset:528 sc1
	s_waitcnt vmcnt(11)
	v_lshlrev_b32_e32 v40, 16, v90
	v_lshlrev_b32_e32 v32, 16, v88
	v_and_b32_e32 v33, 0xffff0000, v88
	v_pk_fma_f32 v[32:33], v[36:37], 0.5, v[32:33] op_sel_hi:[1,0,1]
	v_lshlrev_b64 v[36:37], 12, v[104:105]
	v_lshlrev_b32_e32 v34, 16, v89
	v_and_b32_e32 v35, 0xffff0000, v89
	v_and_b32_e32 v41, 0xffff0000, v90
	v_lshlrev_b32_e32 v42, 16, v91
	v_and_b32_e32 v43, 0xffff0000, v91
	v_lshl_add_u64 v[36:37], s[82:83], 0, v[36:37]
	v_pk_fma_f32 v[34:35], v[38:39], 0.5, v[34:35] op_sel_hi:[1,0,1]
	v_pk_fma_f32 v[30:31], v[30:31], 0.5, v[42:43] op_sel_hi:[1,0,1]
	v_pk_fma_f32 v[28:29], v[28:29], 0.5, v[40:41] op_sel_hi:[1,0,1]
	v_lshl_add_u64 v[36:37], v[36:37], 0, v[124:125]
	global_store_dwordx4 v[36:37], v[32:35], off sc1
	global_store_dwordx4 v[36:37], v[28:31], off offset:16 sc1
	s_waitcnt vmcnt(12)
	v_lshlrev_b32_e32 v32, 16, v94
	v_lshlrev_b32_e32 v28, 16, v92
	v_and_b32_e32 v29, 0xffff0000, v92
	v_lshlrev_b32_e32 v30, 16, v93
	v_and_b32_e32 v31, 0xffff0000, v93
	v_and_b32_e32 v33, 0xffff0000, v94
	v_lshlrev_b32_e32 v34, 16, v95
	v_and_b32_e32 v35, 0xffff0000, v95
	v_pk_fma_f32 v[26:27], v[26:27], 0.5, v[30:31] op_sel_hi:[1,0,1]
	v_pk_fma_f32 v[24:25], v[24:25], 0.5, v[28:29] op_sel_hi:[1,0,1]
	v_pk_fma_f32 v[16:17], v[16:17], 0.5, v[32:33] op_sel_hi:[1,0,1]
	v_pk_fma_f32 v[18:19], v[18:19], 0.5, v[34:35] op_sel_hi:[1,0,1]
	global_store_dwordx4 v[36:37], v[24:27], off offset:512 sc1
	global_store_dwordx4 v[36:37], v[16:19], off offset:528 sc1
	s_waitcnt vmcnt(13)
	v_lshlrev_b32_e32 v24, 16, v98
	v_lshlrev_b32_e32 v16, 16, v96
	v_and_b32_e32 v17, 0xffff0000, v96
	v_pk_fma_f32 v[16:17], v[20:21], 0.5, v[16:17] op_sel_hi:[1,0,1]
	v_lshlrev_b64 v[20:21], 12, v[106:107]
	v_lshlrev_b32_e32 v18, 16, v97
	v_and_b32_e32 v19, 0xffff0000, v97
	v_and_b32_e32 v25, 0xffff0000, v98
	v_lshlrev_b32_e32 v26, 16, v99
	v_and_b32_e32 v27, 0xffff0000, v99
	v_lshl_add_u64 v[20:21], s[82:83], 0, v[20:21]
	v_pk_fma_f32 v[18:19], v[22:23], 0.5, v[18:19] op_sel_hi:[1,0,1]
	v_pk_fma_f32 v[14:15], v[14:15], 0.5, v[26:27] op_sel_hi:[1,0,1]
	v_pk_fma_f32 v[12:13], v[12:13], 0.5, v[24:25] op_sel_hi:[1,0,1]
	v_lshl_add_u64 v[20:21], v[20:21], 0, v[124:125]
	global_store_dwordx4 v[20:21], v[16:19], off sc1
	global_store_dwordx4 v[20:21], v[12:15], off offset:16 sc1
	s_waitcnt vmcnt(14)
	v_lshlrev_b32_e32 v16, 16, v70
	v_lshlrev_b32_e32 v12, 16, v68
	v_and_b32_e32 v13, 0xffff0000, v68
	v_lshlrev_b32_e32 v14, 16, v69
	v_and_b32_e32 v15, 0xffff0000, v69
	v_and_b32_e32 v17, 0xffff0000, v70
	v_lshlrev_b32_e32 v18, 16, v71
	v_and_b32_e32 v19, 0xffff0000, v71
	v_pk_fma_f32 v[10:11], v[10:11], 0.5, v[14:15] op_sel_hi:[1,0,1]
	v_pk_fma_f32 v[8:9], v[8:9], 0.5, v[12:13] op_sel_hi:[1,0,1]
	v_pk_fma_f32 v[6:7], v[6:7], 0.5, v[18:19] op_sel_hi:[1,0,1]
	v_pk_fma_f32 v[4:5], v[4:5], 0.5, v[16:17] op_sel_hi:[1,0,1]
	global_store_dwordx4 v[20:21], v[8:11], off offset:512 sc1
	global_store_dwordx4 v[20:21], v[4:7], off offset:528 sc1
	s_waitcnt lgkmcnt(0)
	s_barrier
	s_cbranch_vccnz .LBB0_583
	s_andn2_b64 vcc, exec, s[14:15]
	s_cbranch_vccnz .LBB0_582
	s_barrier
	s_branch .LBB0_582
